# DP3: phase 0 keeps layer-0 w_in + the 32 adaLN blocks needed by the first norm + rope alone on one workgroup; the other 64 layer-0 adaLN blocks move to the idle workgroups of L0 sub1
# baseline (speedup 1.0000x reference)
; __device__ void phase_prep(const Params& p, LAS unsigned char* lds) {
;     ...
;     constexpr int I_TR = 2 * T_L, I_POOL = I_TR + 128, I_FOUR = I_POOL + 256, I_MOD = I_FOUR + 192, I_ALL = I_MOD + 1;
;     for (int prep_rep = 0; prep_rep < ((PROBE >= 301 && PROBE <= 304) ? 2 : 1); ++prep_rep)
;     for (int it = blockIdx.x; it < I_ALL; it += gridDim.x) {
;     ...
;         if (prep_rep == 1) { const int cls = (it < I_TR) ? 301 : (it < I_FOUR) ? 302 : (it < I_MOD) ? 303 : 304; if (cls != PROBE) continue; }
;     ...
;         if (it < I_TR) {
.LBB0_14:
	s_andn2_b64 vcc, exec, s[0:1]
	s_cbranch_vccnz .LBB0_735
	v_writelane_b32 v252, s26, 1
	s_movk_i32 s1, 256
	v_writelane_b32 v252, s1, 2
	s_movk_i32 s1, 305
	v_writelane_b32 v252, s1, 3
	s_movk_i32 s1, 0
	v_writelane_b32 v252, s1, 0
	s_movk_i32 s1, 49
	v_writelane_b32 v252, s1, 5
	s_movk_i32 s1, 2127
	v_writelane_b32 v252, s1, 6
	s_movk_i32 s1, 81
	v_writelane_b32 v252, s1, 7
	s_movk_i32 s1, -32
	v_writelane_b32 v252, s1, 8
	s_movk_i32 s1, 255
	v_writelane_b32 v252, s1, 9
	s_movk_i32 s1, 2113
	v_writelane_b32 v252, s1, 10
	s_movk_i32 s1, 256
	v_writelane_b32 v252, s1, 11
	s_movk_i32 s1, -33
	v_writelane_b32 v252, s1, 12
	s_branch .LBB0_650

; __device__ void phase_prep(const Params& p, LAS unsigned char* lds) {
;     ...
;     constexpr int I_TR = 2 * T_L, I_POOL = I_TR + 128, I_FOUR = I_POOL + 256, I_MOD = I_FOUR + 192, I_ALL = I_MOD + 1;
;     for (int prep_rep = 0; prep_rep < ((PROBE >= 301 && PROBE <= 304) ? 2 : 1); ++prep_rep)
;     for (int it = blockIdx.x; it < I_ALL; it += gridDim.x) {
;     ...
;         if (prep_rep == 1) { const int cls = (it < I_TR) ? 301 : (it < I_FOUR) ? 302 : (it < I_MOD) ? 303 : 304; if (cls != PROBE) continue; }
;     ...
;         if (it < I_TR) {
.Lmy_dp_m0:
	s_cmp_lt_u32 s26, 132
	s_cbranch_scc1 .LBB0_735
	s_sub_i32 s0, s26, 132
	v_writelane_b32 v252, s0, 1
	s_movk_i32 s1, 124
	v_writelane_b32 v252, s1, 2
	s_movk_i32 s1, 352
	v_writelane_b32 v252, s1, 3
	s_movk_i32 s1, 272
	v_writelane_b32 v252, s1, 0
	s_movk_i32 s1, 96
	v_writelane_b32 v252, s1, 5
	s_movk_i32 s1, 1696
	v_writelane_b32 v252, s1, 6
	s_movk_i32 s1, 160
	v_writelane_b32 v252, s1, 7
	s_movk_i32 s1, 1760
	v_writelane_b32 v252, s1, 8
	s_movk_i32 s1, 288
	v_writelane_b32 v252, s1, 9
	s_movk_i32 s1, 1920
	v_writelane_b32 v252, s1, 10
	s_movk_i32 s1, 32767
	v_writelane_b32 v252, s1, 11
	s_movk_i32 s1, 0
	v_writelane_b32 v252, s1, 12
	s_branch .LBB0_650
.Lmy_dp_m1:
	s_cmp_lt_u32 s26, 16
	s_cbranch_scc1 .LBB0_735
	s_sub_i32 s0, s26, 16
	v_writelane_b32 v252, s0, 1
	s_movk_i32 s1, 240
	v_writelane_b32 v252, s1, 2
	s_movk_i32 s1, 992
	v_writelane_b32 v252, s1, 3
	s_movk_i32 s1, 368
	v_writelane_b32 v252, s1, 0
	s_movk_i32 s1, 896
	v_writelane_b32 v252, s1, 5
	s_movk_i32 s1, 1376
	v_writelane_b32 v252, s1, 6
	s_movk_i32 s1, 32767
	v_writelane_b32 v252, s1, 7
	s_movk_i32 s1, 0
	v_writelane_b32 v252, s1, 8
	s_movk_i32 s1, 32767
	v_writelane_b32 v252, s1, 9
	s_movk_i32 s1, 0
	v_writelane_b32 v252, s1, 10
	s_movk_i32 s1, 32767
	v_writelane_b32 v252, s1, 11
	s_movk_i32 s1, 0
	v_writelane_b32 v252, s1, 12
	s_branch .LBB0_650
.Lmy_dp_m2:
	s_cmp_lt_u32 s26, 84
	s_cbranch_scc1 .LBB0_735
	s_sub_i32 s0, s26, 84
	v_writelane_b32 v252, s0, 1
	s_movk_i32 s1, 172
	v_writelane_b32 v252, s1, 2
	s_movk_i32 s1, 720
	v_writelane_b32 v252, s1, 3
	s_movk_i32 s1, 1264
	v_writelane_b32 v252, s1, 0
	s_movk_i32 s1, 528
	v_writelane_b32 v252, s1, 5
	s_movk_i32 s1, 1328
	v_writelane_b32 v252, s1, 6
	s_movk_i32 s1, 592
	v_writelane_b32 v252, s1, 7
	s_movk_i32 s1, 1456
	v_writelane_b32 v252, s1, 8
	s_movk_i32 s1, 32767
	v_writelane_b32 v252, s1, 9
	s_movk_i32 s1, 0
	v_writelane_b32 v252, s1, 10
	s_movk_i32 s1, 32767
	v_writelane_b32 v252, s1, 11
	s_movk_i32 s1, 0
	v_writelane_b32 v252, s1, 12
	s_branch .LBB0_650

; __device__ void phase_prep(const Params& p, LAS unsigned char* lds) {
;     ...
;     for (int it = blockIdx.x; it < I_ALL; it += gridDim.x) {
;     ...
;         if (prep_rep == 1) { const int cls = (it < I_TR) ? 301 : (it < I_FOUR) ? 302 : (it < I_MOD) ? 303 : 304; if (cls != PROBE) continue; }
;     ...
;         if (it < I_TR) {
;             const int l = it / T_L; int j = it % T_L;
;             unsigned char* wb = p.ws + OFF_W + (size_t)l * LW;
.Lmy_dp_first:
	v_readlane_b32 s88, v252, 1
	v_readlane_b32 s89, v252, 3
	s_nop 3
	s_cmp_ge_i32 s88, s89
	s_cbranch_scc1 .LBB0_734
	v_readlane_b32 s17, v252, 0
	v_readlane_b32 s89, v252, 5
	s_nop 3
	s_cmp_lt_i32 s88, s89
	s_cbranch_scc1 .Lmy_dp_it
	v_readlane_b32 s17, v252, 6
	v_readlane_b32 s89, v252, 7
	s_nop 3
	s_cmp_lt_i32 s88, s89
	s_cbranch_scc1 .Lmy_dp_it
	v_readlane_b32 s17, v252, 8
	v_readlane_b32 s89, v252, 9
	s_nop 3
	s_cmp_lt_i32 s88, s89
	s_cbranch_scc1 .Lmy_dp_it
	v_readlane_b32 s17, v252, 10
	v_readlane_b32 s89, v252, 11
	s_nop 3
	s_cmp_lt_i32 s88, s89
	s_cbranch_scc1 .Lmy_dp_it
	v_readlane_b32 s17, v252, 12
	s_nop 3
